# v63 plus the first grid barrier reads the 16 per-XCD arrival counts with one batch of loads instead of 12 serialised round trips
# speedup vs baseline: 1.0008x; 1.0008x over previous
.LBB0_256:
	s_waitcnt lgkmcnt(0)
	global_load_dword v0, v97, s[68:69] sc1
	global_load_dword v1, v97, s[68:69] offset:256 sc1
	global_load_dword v2, v97, s[68:69] offset:512 sc1
	global_load_dword v3, v97, s[68:69] offset:768 sc1
	global_load_dword v4, v97, s[68:69] offset:1024 sc1
	global_load_dword v5, v97, s[68:69] offset:1280 sc1
	global_load_dword v6, v97, s[68:69] offset:1536 sc1
	global_load_dword v7, v97, s[68:69] offset:1792 sc1
	global_load_dword v8, v97, s[68:69] offset:2048 sc1
	global_load_dword v9, v97, s[68:69] offset:2304 sc1
	global_load_dword v10, v97, s[68:69] offset:2560 sc1
	global_load_dword v11, v97, s[68:69] offset:2816 sc1
	global_load_dword v12, v97, s[68:69] offset:3072 sc1
	global_load_dword v13, v97, s[68:69] offset:3328 sc1
	global_load_dword v14, v97, s[68:69] offset:3584 sc1
	global_load_dword v15, v97, s[68:69] offset:3840 sc1
	s_mov_b64 s[14:15], -1
	s_mov_b64 s[12:13], -1
	s_waitcnt vmcnt(0)
	v_add_u32_e32 v16, v1, v0
	v_add_u32_e32 v16, v16, v2
	v_add_u32_e32 v16, v16, v3
	v_add_u32_e32 v16, v16, v4
	v_add_u32_e32 v16, v16, v5
	v_add_u32_e32 v16, v16, v6
	v_add_u32_e32 v16, v16, v7
	v_add_u32_e32 v16, v16, v8
	v_add_u32_e32 v16, v16, v9
	v_add_u32_e32 v16, v16, v10
	v_add_u32_e32 v16, v16, v11
	v_add_u32_e32 v16, v16, v12
	v_add_u32_e32 v16, v16, v13
	v_add_u32_e32 v16, v16, v14
	v_add_u32_e32 v16, v16, v15
	v_cmp_eq_u32_e32 vcc, s53, v16
	s_cbranch_vccnz .LBB0_255
	s_and_b32 s12, s22, 0xff
	s_cmp_eq_u32 s12, 0
	s_mov_b64 s[12:13], -1
	s_mov_b64 s[18:19], -1
	s_sleep 1
	s_cbranch_scc1 .LBB0_260
	s_and_b64 vcc, exec, s[18:19]
	s_cbranch_vccz .LBB0_255
